# P2: pooling deltas done by the idle attention waves (two tasks each) so conversion waves go straight to the grid barrier
# speedup vs baseline: 1.0128x; 1.0128x over previous
; __device__ __forceinline__ void phase2(LAS unsigned char* lds, int wave) {
;     ...
;     bf16_t* D = (bf16_t*)(ws + WS_D);
;     const int gt = blockIdx.x * 512 + tid, NT = gridDim.x * 512;
;     for (int T = gt; T < 512 * 256; T += NT) {
;         const int grp = __builtin_amdgcn_readfirstlane(((T & 255) * 8) >> 9);
;         if (grp == 0) pool_prompt_task<2, 16>(Ub, D, T, 0); else if (grp == 1) pool_prompt_task<4, 16>(Ub, D, T, 0); else if (grp == 2) pool_prompt_task<8, 16>(Ub, D, T, 0); else { pool_prompt_task<16, 8>(Ub, D, T, 0); pool_prompt_task<16, 8>(Ub, D, T, 8); }
;     }
.LBB0_550:
	s_waitcnt lgkmcnt(0)
	s_add_u32 s8, s16, 0x1e800000
	s_addc_u32 s9, s17, 0
	s_add_u32 s10, s16, 0x22a00000
	s_load_dword s3, s[50:51], 0x0
	s_addc_u32 s11, s17, 0
	s_and_b32 s4, 0xffff, s4
	s_cmp_lg_u32 s4, 0
	s_cselect_b64 s[4:5], -1, 0
	s_cmp_lg_u64 s[4:5], 0
	v_lshl_add_u32 v138, s2, 9, v193
	v_lshrrev_b32_e32 v139, 8, v193
	v_lshl_add_u32 v138, v139, 20, v138
	s_waitcnt lgkmcnt(0)
	s_addc_u32 s3, s3, 0
	s_mov_b32 s4, 0x20000
	s_lshl_b32 s17, s3, 9
	v_cmp_gt_i32_e32 vcc, s4, v138
	v_lshlrev_b32_e32 v139, 3, v138
	s_and_saveexec_b64 s[12:13], vcc
	s_cbranch_execz .LBB0_640
	v_lshlrev_b32_e32 v140, 3, v138
	s_lshl_b32 s19, s3, 12
	s_mov_b64 s[14:15], 0
	v_mov_b32_e32 v97, 0
	s_movk_i32 s21, 0x1000
	s_movk_i32 s24, 0x2000
	s_movk_i32 s25, 0x3000
	s_mov_b32 s16, 0x3d800000
	s_mov_b32 s18, 0x3e000000
	s_mov_b32 s20, 0x3e800000
	s_lshl_b32 s26, s2, 9
	s_or_b32 s26, s26, 0x1ff
	v_mov_b32_e32 v141, v138
	s_branch .LBB0_554

; __device__ __forceinline__ void phase2(LAS unsigned char* lds, int wave) {
;     ...
;     for (int T = gt; T < 512 * 256; T += NT) {
;         const int grp = __builtin_amdgcn_readfirstlane(((T & 255) * 8) >> 9);
;         if (grp == 0) pool_prompt_task<2, 16>(Ub, D, T, 0); else if (grp == 1) pool_prompt_task<4, 16>(Ub, D, T, 0); else if (grp == 2) pool_prompt_task<8, 16>(Ub, D, T, 0); else { pool_prompt_task<16, 8>(Ub, D, T, 0); pool_prompt_task<16, 8>(Ub, D, T, 8); }
.LBB0_553:
	v_add_u32_e32 v141, 0x100, v141
	v_cmp_lt_i32_e32 vcc, s26, v141
	s_or_b64 s[14:15], vcc, s[14:15]
	v_add_u32_e32 v140, 0x800, v140
	s_andn2_b64 exec, exec, s[14:15]
	s_cbranch_execz .LBB0_640

; #define KIN(i) ((const float*)karg(i))
; __device__ __forceinline__ void phase2(LAS unsigned char* lds, int wave) {
;     ...
;     for (int T = gt; T < 256 * 256; T += NT) {
;         const int grp = __builtin_amdgcn_readfirstlane(((T & 255) * 8) >> 9);
;         if (grp == 0) pool_sample_task<2>(Ub, KIN(4), D, T); else if (grp == 1) pool_sample_task<4>(Ub, KIN(4), D, T); else if (grp == 2) pool_sample_task<8>(Ub, KIN(4), D, T); else pool_sample_task<16>(Ub, KIN(4), D, T);
.LBB0_640:
	s_or_b64 exec, exec, s[12:13]
	s_mov_b32 s4, 0x10000
	v_cmp_gt_i32_e32 vcc, s4, v138
	s_and_saveexec_b64 s[6:7], vcc
	s_cbranch_execz .LBB0_758
	s_lshl_b32 s3, s3, 12
	s_mov_b64 s[12:13], 0
	v_mov_b32_e32 v125, 0
	s_mov_b32 s14, 0x3d800000
	s_mov_b32 s16, 0x3e000000
	s_mov_b64 s[18:19], 0x1c000
	s_mov_b32 s20, 0x3e800000
	s_movk_i32 s4, 0x2100
	s_lshl_b32 s5, s2, 9
	s_or_b32 s5, s5, 0x1ff
	v_mov_b32_e32 v132, 0x1ff1
	v_mov_b32_e32 v133, 0x2000
	s_branch .LBB0_644

; #define KIN(i) ((const float*)karg(i))
; __device__ __forceinline__ unsigned pk2(float lo, float hi) { const bf16x2_t v = __builtin_convertvector((f32x2_t){lo, hi}, bf16x2_t); return __builtin_bit_cast(unsigned, v); }
; template <int W>
; __device__ __forceinline__ void pool_sample_task(const bf16_t* Ub, const float* sp, bf16_t* D, int T) {
;     ...
;     u32x4 o; o.x = pk2(s[0] * ic - x[0][0], s[1] * ic - x[0][1]); o.y = pk2(s[2] * ic - x[0][2], s[3] * ic - x[0][3]); o.z = pk2(s[4] * ic - x[0][4], s[5] * ic - x[0][5]); o.w = pk2(s[6] * ic - x[0][6], s[7] * ic - x[0][7]);
;     *(u32x4*)(D + ((size_t)grp * NTOK + NPROMPT + row) * 512 + (ch0 & 511)) = o;
; __device__ __forceinline__ void phase2(LAS unsigned char* lds, int wave) {
;     ...
;     for (int T = gt; T < 256 * 256; T += NT) {
;         const int grp = __builtin_amdgcn_readfirstlane(((T & 255) * 8) >> 9);
;         if (grp == 0) pool_sample_task<2>(Ub, KIN(4), D, T); else if (grp == 1) pool_sample_task<4>(Ub, KIN(4), D, T); else if (grp == 2) pool_sample_task<8>(Ub, KIN(4), D, T); else pool_sample_task<16>(Ub, KIN(4), D, T);
.LBB0_643:
	s_waitcnt vmcnt(0)
	v_lshrrev_b32_e32 v6, 9, v127
	v_mad_u32_u24 v124, v6, s4, v133
	v_ashrrev_i32_e32 v127, 31, v126
	v_cvt_pk_bf16_f32 v3, v4, v5
	v_lshl_add_u64 v[4:5], v[124:125], 0, v[126:127]
	v_lshlrev_b64 v[4:5], 10, v[4:5]
	v_and_b32_e32 v6, 0x1f8, v139
	v_add_u32_e32 v138, 0x100, v138
	v_lshl_add_u64 v[4:5], s[10:11], 0, v[4:5]
	v_lshlrev_b32_e32 v124, 1, v6
	v_cmp_lt_i32_e32 vcc, s5, v138
	v_lshl_add_u64 v[4:5], v[4:5], 0, v[124:125]
	s_or_b64 s[12:13], vcc, s[12:13]
	v_add_u32_e32 v139, 0x800, v139
	flat_store_dwordx4 v[4:5], v[0:3]
	s_andn2_b64 exec, exec, s[12:13]
	s_cbranch_execz .LBB0_758
